# plus: softmax denominator reductions via permlane swaps too; lgkmcnt waits of the sliding-window head loop re-derived
# baseline (speedup 1.0000x reference)
.LBB0_189:
	v_readlane_b32 s4, v244, 10
	s_xor_b64 s[2:3], s[2:3], -1
	s_lshl_b64 s[94:95], s[90:91], 2
	v_readlane_b32 s16, v244, 22
	v_readlane_b32 s17, v244, 23
	s_add_u32 s94, s16, s94
	s_addc_u32 s95, s17, s95
	ds_read_b128 v[134:137], v117
	ds_read_b128 v[138:141], v117 offset:64
	global_load_dword v99, v3, s[94:95]
	ds_read_b128 v[142:145], v118
	ds_read_b128 v[146:149], v118 offset:64
	s_waitcnt lgkmcnt(3)
	v_mfma_f32_16x16x32_bf16 v[134:137], v[134:137], v[72:75], 0
	v_readlane_b32 s6, v244, 12
	v_readlane_b32 s7, v244, 13
	s_mov_b32 s4, 0xf149f2ca
	s_waitcnt lgkmcnt(1)
	v_mfma_f32_16x16x32_bf16 v[142:145], v[142:145], v[72:75], 0
	v_readlane_b32 s6, v243, 12
	v_mov_b32_e32 v100, s4
	v_readlane_b32 s7, v243, 13
	v_mfma_f32_16x16x32_bf16 v[134:137], v[138:141], v[68:71], v[134:137]
	ds_read_b128 v[138:141], v119
	v_mov_b32_e32 v178, s4
	v_mov_b32_e32 v216, s4
	s_waitcnt lgkmcnt(1)
	v_mfma_f32_16x16x32_bf16 v[142:145], v[146:149], v[68:71], v[142:145]
	ds_read_b128 v[146:149], v119 offset:64
	ds_read_b128 v[150:153], v120
	ds_read_b128 v[154:157], v120 offset:64
	ds_read_b128 v[158:161], v121
	ds_read_b128 v[162:165], v121 offset:64
	v_cndmask_b32_e64 v100, v100, v134, s[6:7]
	s_waitcnt lgkmcnt(5)
	v_mfma_f32_16x16x32_bf16 v[138:141], v[138:141], v[72:75], 0
	v_readlane_b32 s6, v243, 14
	v_readlane_b32 s7, v243, 15
	v_mov_b32_e32 v218, s4
	s_waitcnt lgkmcnt(1)
	v_mfma_f32_16x16x32_bf16 v[158:161], v[158:161], v[72:75], 0
	v_mov_b32_e32 v220, s4
	v_mov_b32_e32 v222, s4
	v_readlane_b32 s5, v244, 11
	v_mfma_f32_16x16x32_bf16 v[138:141], v[146:149], v[68:71], v[138:141]
	ds_read_b128 v[146:149], v122
	ds_read_b128 v[166:169], v122 offset:64
	ds_read_b128 v[170:173], v123
	ds_read_b128 v[174:177], v123 offset:64
	ds_read_b128 v[196:199], v124
	ds_read_b128 v[200:203], v124 offset:64
	ds_read_b128 v[204:207], v125
	ds_read_b128 v[208:211], v125 offset:64
	v_readlane_b32 s8, v244, 14
	s_waitcnt lgkmcnt(8)
	v_mfma_f32_16x16x32_bf16 v[158:161], v[162:165], v[68:71], v[158:161]
	v_cndmask_b32_e64 v163, v184, v135, s[6:7]
	v_readlane_b32 s6, v243, 16
	v_readlane_b32 s7, v243, 17
	s_waitcnt lgkmcnt(7)
	v_mfma_f32_16x16x32_bf16 v[146:149], v[146:149], v[72:75], 0
	v_mov_b32_e32 v162, s4
	v_cndmask_b32_e64 v165, v184, v136, s[6:7]
	v_readlane_b32 s6, v243, 18
	v_readlane_b32 s7, v243, 19
	s_waitcnt lgkmcnt(6)
	v_mfma_f32_16x16x32_bf16 v[146:149], v[166:169], v[68:71], v[146:149]
	v_cndmask_b32_e64 v158, v162, v158, s[36:37]
	v_cndmask_b32_e64 v166, v184, v137, s[6:7]
	v_readlane_b32 s6, v243, 20
	v_readlane_b32 s7, v243, 21
	v_mfma_f32_16x16x32_bf16 v[150:153], v[150:153], v[72:75], 0
	v_cndmask_b32_e64 v159, v184, v159, s[38:39]
	v_cndmask_b32_e64 v167, v178, v142, s[6:7]
	v_readlane_b32 s6, v243, 22
	v_readlane_b32 s7, v243, 23
	v_mfma_f32_16x16x32_bf16 v[150:153], v[154:157], v[68:71], v[150:153]
	ds_read_b128 v[154:157], v126
	ds_read_b128 v[212:215], v126 offset:64
	v_cndmask_b32_e64 v168, v184, v143, s[6:7]
	v_readlane_b32 s6, v243, 24
	v_readlane_b32 s7, v243, 25
	s_waitcnt lgkmcnt(7)
	v_mfma_f32_16x16x32_bf16 v[134:137], v[170:173], v[72:75], 0
	v_cndmask_b32_e64 v171, v216, v138, s[0:1]
	v_cndmask_b32_e64 v169, v184, v144, s[6:7]
	v_readlane_b32 s6, v243, 26
	v_readlane_b32 s7, v243, 27
	s_waitcnt lgkmcnt(6)
	v_mfma_f32_16x16x32_bf16 v[134:137], v[174:177], v[68:71], v[134:137]
	v_cndmask_b32_e64 v172, v184, v139, s[20:21]
	v_cndmask_b32_e64 v170, v184, v145, s[6:7]
	v_cndmask_b32_e64 v173, v184, v140, s[22:23]
	s_waitcnt lgkmcnt(5)
	v_mfma_f32_16x16x32_bf16 v[142:145], v[196:199], v[72:75], 0
	v_cndmask_b32_e64 v174, v184, v141, s[24:25]
	v_cndmask_b32_e64 v150, v218, v150, s[26:27]
	v_cndmask_b32_e64 v151, v184, v151, s[28:29]
	s_waitcnt lgkmcnt(4)
	v_mfma_f32_16x16x32_bf16 v[138:141], v[200:203], v[68:71], v[142:145]
	v_cndmask_b32_e64 v152, v184, v152, s[30:31]
	v_cndmask_b32_e64 v153, v184, v153, s[34:35]
	v_mov_b32_e32 v164, s4
	s_waitcnt lgkmcnt(3)
	v_mfma_f32_16x16x32_bf16 v[142:145], v[204:207], v[72:75], 0
	v_cndmask_b32_e64 v160, v184, v160, s[40:41]
	v_cndmask_b32_e64 v161, v184, v161, s[42:43]
	v_cndmask_b32_e64 v146, v164, v146, s[44:45]
	s_waitcnt lgkmcnt(1)
	v_mfma_f32_16x16x32_bf16 v[72:75], v[154:157], v[72:75], 0
	v_cndmask_b32_e64 v147, v184, v147, s[46:47]
	v_cndmask_b32_e64 v148, v184, v148, s[48:49]
	v_cndmask_b32_e64 v149, v184, v149, s[50:51]
	v_mfma_f32_16x16x32_bf16 v[142:145], v[208:211], v[68:71], v[142:145]
	v_cndmask_b32_e64 v134, v220, v134, s[52:53]
	v_cndmask_b32_e64 v135, v184, v135, s[54:55]
	v_readlane_b32 s9, v244, 15
	s_waitcnt lgkmcnt(0)
	v_mfma_f32_16x16x32_bf16 v[68:71], v[212:215], v[68:71], v[72:75]
	v_readlane_b32 s10, v244, 16
	s_nop 1
	v_cndmask_b32_e64 v154, v184, v143, s[70:71]
	v_cndmask_b32_e64 v155, v184, v144, s[72:73]
	s_waitcnt vmcnt(0)
	v_mul_f32_e32 v72, 0x3fb8aa3b, v99
	v_max3_f32 v72, v72, v100, v163
	v_max3_f32 v72, v72, v165, v166
	v_max3_f32 v72, v72, v167, v168
	v_max3_f32 v72, v72, v169, v170
	v_max3_f32 v72, v72, v171, v172
	v_max3_f32 v72, v72, v173, v174
	v_max3_f32 v72, v72, v150, v151
	v_max3_f32 v72, v72, v152, v153
	v_max3_f32 v72, v72, v158, v159
	v_max3_f32 v72, v72, v160, v161
	v_max3_f32 v72, v72, v146, v147
	v_max3_f32 v72, v72, v148, v149
	v_cndmask_b32_e64 v73, v184, v136, s[56:57]
	v_cndmask_b32_e64 v74, v184, v137, s[58:59]
	v_max3_f32 v72, v72, v134, v135
	v_cndmask_b32_e64 v75, v222, v138, s[60:61]
	v_cndmask_b32_e64 v136, v184, v139, s[62:63]
	v_max3_f32 v72, v72, v73, v74
	v_max3_f32 v72, v72, v75, v136
	v_cndmask_b32_e64 v137, v184, v140, s[64:65]
	v_cndmask_b32_e64 v138, v184, v141, s[66:67]
	v_max3_f32 v139, v72, v137, v138
	v_mov_b32_e32 v72, s4
	v_cndmask_b32_e64 v140, v72, v142, s[68:69]
	v_max3_f32 v72, v139, v140, v154
	v_cndmask_b32_e64 v162, v184, v145, s[74:75]
	v_max3_f32 v139, v72, v155, v162
	v_mov_b32_e32 v72, s4
	v_cndmask_b32_e64 v164, v72, v68, s[76:77]
	v_cndmask_b32_e64 v175, v184, v69, s[78:79]
	v_max3_f32 v68, v139, v164, v175
	v_cndmask_b32_e64 v176, v184, v70, s[80:81]
	v_cndmask_b32_e64 v177, v184, v71, s[82:83]
	v_max3_f32 v68, v68, v176, v177
	v_mov_b32_e32 v69, v68
	s_nop 1
	v_permlane16_swap_b32 v69, v68
	s_mov_b32 s4, 0x3fb8aa3b
	v_readlane_b32 s11, v244, 17
	v_readlane_b32 s12, v244, 18
	v_readlane_b32 s13, v244, 19
	v_max_f32_e32 v69, v69, v69
	v_max_f32_e32 v68, v68, v69
	v_mov_b32_e32 v69, v68
	s_nop 1
	v_permlane32_swap_b32 v69, v68
	v_readlane_b32 s14, v244, 20
	v_readlane_b32 s15, v244, 21
	v_readlane_b32 s18, v244, 24
	v_readlane_b32 s19, v244, 25
	v_max_f32_e32 v69, v69, v69
	v_max_f32_e32 v178, v68, v69
	v_sub_f32_e32 v68, v100, v178
	v_exp_f32_e32 v72, v68
	v_sub_f32_e32 v68, v163, v178
	v_exp_f32_e32 v100, v68
	v_sub_f32_e32 v69, v165, v178
	v_exp_f32_e32 v139, v69
	v_sub_f32_e32 v69, v166, v178
	v_exp_f32_e32 v141, v69
	v_sub_f32_e32 v69, v167, v178
	v_add_f32_e32 v68, 0, v72
	v_exp_f32_e32 v142, v69
	v_sub_f32_e32 v69, v168, v178
	v_add_f32_e32 v68, v100, v68
	v_exp_f32_e32 v143, v69
	v_sub_f32_e32 v69, v169, v178
	v_add_f32_e32 v68, v139, v68
	v_exp_f32_e32 v144, v69
	v_sub_f32_e32 v69, v170, v178
	v_add_f32_e32 v68, v141, v68
	v_exp_f32_e32 v145, v69
	v_sub_f32_e32 v69, v171, v178
	v_add_f32_e32 v68, v142, v68
	v_exp_f32_e32 v156, v69
	v_sub_f32_e32 v69, v172, v178
	v_add_f32_e32 v68, v143, v68
	v_exp_f32_e32 v157, v69
	v_sub_f32_e32 v69, v173, v178
	v_add_f32_e32 v68, v144, v68
	v_exp_f32_e32 v163, v69
	v_sub_f32_e32 v69, v174, v178
	v_add_f32_e32 v68, v145, v68
	v_exp_f32_e32 v165, v69
	v_sub_f32_e32 v69, v150, v178
	v_add_f32_e32 v68, v156, v68
	v_exp_f32_e32 v166, v69
	v_sub_f32_e32 v69, v151, v178
	v_add_f32_e32 v68, v157, v68
	v_exp_f32_e32 v167, v69
	v_sub_f32_e32 v69, v152, v178
	v_add_f32_e32 v68, v163, v68
	v_exp_f32_e32 v168, v69
	v_sub_f32_e32 v69, v153, v178
	v_add_f32_e32 v68, v165, v68
	v_exp_f32_e32 v169, v69
	v_sub_f32_e32 v69, v158, v178
	v_add_f32_e32 v68, v166, v68
	v_exp_f32_e32 v158, v69
	v_sub_f32_e32 v69, v159, v178
	v_add_f32_e32 v68, v167, v68
	v_exp_f32_e32 v159, v69
	v_sub_f32_e32 v69, v160, v178
	v_add_f32_e32 v68, v168, v68
	v_exp_f32_e32 v160, v69
	v_sub_f32_e32 v69, v161, v178
	v_add_f32_e32 v68, v169, v68
	v_exp_f32_e32 v161, v69
	v_sub_f32_e32 v69, v146, v178
	v_add_f32_e32 v68, v158, v68
	v_exp_f32_e32 v170, v69
	v_sub_f32_e32 v69, v147, v178
	v_add_f32_e32 v68, v159, v68
	v_exp_f32_e32 v171, v69
	v_sub_f32_e32 v69, v148, v178
	v_add_f32_e32 v68, v160, v68
	v_exp_f32_e32 v172, v69
	v_sub_f32_e32 v69, v149, v178
	v_add_f32_e32 v68, v161, v68
	v_exp_f32_e32 v173, v69
	v_sub_f32_e32 v69, v134, v178
	v_add_f32_e32 v68, v170, v68
	v_exp_f32_e32 v174, v69
	v_sub_f32_e32 v69, v135, v178
	v_add_f32_e32 v68, v171, v68
	v_exp_f32_e32 v179, v69
	v_sub_f32_e32 v69, v73, v178
	v_add_f32_e32 v68, v172, v68
	v_exp_f32_e32 v195, v69
	v_sub_f32_e32 v69, v74, v178
	v_add_f32_e32 v68, v173, v68
	v_exp_f32_e32 v196, v69
	v_sub_f32_e32 v69, v75, v178
	v_add_f32_e32 v68, v174, v68
	v_exp_f32_e32 v197, v69
	v_sub_f32_e32 v69, v136, v178
	v_add_f32_e32 v68, v179, v68
	v_exp_f32_e32 v198, v69
	v_add_f32_e32 v68, v195, v68
	v_add_f32_e32 v68, v196, v68
	v_add_f32_e32 v68, v197, v68
	v_add_f32_e32 v146, v198, v68
	v_sub_f32_e32 v68, v137, v178
	v_exp_f32_e32 v199, v68
	v_sub_f32_e32 v68, v138, v178
	v_add_u32_e32 v74, 0xb000, v127
	v_exp_f32_e32 v200, v68
	v_add_u32_e32 v68, 0x9000, v127
	v_cvt_pk_bf16_f32 v72, v72, v100
	ds_read_b128 v[134:137], v74 offset:256
	v_cvt_pk_bf16_f32 v74, v142, v143
	v_add_u32_e32 v100, 0xd000, v127
	v_add_u32_e32 v142, 0xf000, v127
	v_sub_f32_e32 v147, v140, v178
	ds_read_b128 v[68:71], v68
	v_cvt_pk_bf16_f32 v73, v139, v141
	v_cvt_pk_bf16_f32 v75, v144, v145
	ds_read_b128 v[138:141], v100 offset:512
	ds_read_b128 v[142:145], v142 offset:768
	s_waitcnt lgkmcnt(2)
	v_mfma_f32_16x16x32_bf16 v[68:71], v[68:71], v[72:75], 0
	v_exp_f32_e32 v100, v147
	v_add_f32_e32 v146, v199, v146
	v_add_f32_e32 v146, v200, v146
	v_mfma_f32_16x16x32_bf16 v[134:137], v[134:137], v[72:75], 0
	v_add_f32_e32 v201, v100, v146
	v_sub_f32_e32 v146, v154, v178
	v_add_u32_e32 v148, 0xb000, v130
	s_waitcnt lgkmcnt(1)
	v_mfma_f32_16x16x32_bf16 v[138:141], v[138:141], v[72:75], 0
	v_exp_f32_e32 v202, v146
	v_cvt_pk_bf16_f32 v146, v156, v157
	v_cvt_pk_bf16_f32 v147, v163, v165
	s_waitcnt lgkmcnt(0)
	v_mfma_f32_16x16x32_bf16 v[72:75], v[142:145], v[72:75], 0
	v_add_u32_e32 v142, 0x9000, v130
	ds_read_b128 v[142:145], v142
	ds_read_b128 v[150:153], v148 offset:256
	v_cvt_pk_bf16_f32 v148, v166, v167
	v_cvt_pk_bf16_f32 v149, v168, v169
	v_add_u32_e32 v154, 0xd000, v130
	s_waitcnt lgkmcnt(1)
	v_mfma_f32_16x16x32_bf16 v[68:71], v[142:145], v[146:149], v[68:71]
	v_add_u32_e32 v142, 0xf000, v130
	ds_read_b128 v[142:145], v142 offset:768
	v_sub_f32_e32 v203, v155, v178
	ds_read_b128 v[154:157], v154 offset:512
	s_waitcnt lgkmcnt(1)
	v_mfma_f32_16x16x32_bf16 v[72:75], v[142:145], v[146:149], v[72:75]
	v_add_u32_e32 v142, 0x9000, v131
	ds_read_b128 v[142:145], v142
	v_exp_f32_e32 v163, v203
	v_mfma_f32_16x16x32_bf16 v[134:137], v[150:153], v[146:149], v[134:137]
	v_sub_f32_e32 v150, v162, v178
	v_exp_f32_e32 v162, v150
	v_add_f32_e32 v150, v202, v201
	s_waitcnt lgkmcnt(1)
	v_mfma_f32_16x16x32_bf16 v[138:141], v[154:157], v[146:149], v[138:141]
	v_add_f32_e32 v150, v163, v150
	v_add_u32_e32 v148, 0xb000, v131
	v_add_f32_e32 v165, v162, v150
	v_cvt_pk_bf16_f32 v146, v158, v159
	v_cvt_pk_bf16_f32 v147, v160, v161
	ds_read_b128 v[150:153], v148 offset:256
	v_cvt_pk_bf16_f32 v148, v170, v171
	v_cvt_pk_bf16_f32 v149, v172, v173
	v_add_u32_e32 v154, 0xd000, v131
	s_waitcnt lgkmcnt(1)
	v_mfma_f32_16x16x32_bf16 v[68:71], v[142:145], v[146:149], v[68:71]
	v_add_u32_e32 v142, 0xf000, v131
	ds_read_b128 v[142:145], v142 offset:768
	ds_read_b128 v[154:157], v154 offset:512
	s_waitcnt lgkmcnt(1)
	v_mfma_f32_16x16x32_bf16 v[72:75], v[142:145], v[146:149], v[72:75]
	v_add_u32_e32 v142, 0x9000, v132
	ds_read_b128 v[142:145], v142
	v_sub_f32_e32 v164, v164, v178
	v_mfma_f32_16x16x32_bf16 v[134:137], v[150:153], v[146:149], v[134:137]
	v_sub_f32_e32 v150, v175, v178
	v_exp_f32_e32 v160, v150
	v_sub_f32_e32 v150, v176, v178
	s_waitcnt lgkmcnt(1)
	v_mfma_f32_16x16x32_bf16 v[138:141], v[154:157], v[146:149], v[138:141]
	v_add_u32_e32 v148, 0xb000, v132
	v_exp_f32_e32 v161, v150
	ds_read_b128 v[150:153], v148 offset:256
	v_exp_f32_e32 v158, v164
	v_sub_f32_e32 v164, v177, v178
	v_exp_f32_e32 v164, v164
	v_cvt_pk_bf16_f32 v146, v174, v179
	v_add_f32_e32 v159, v158, v165
	v_cvt_pk_bf16_f32 v147, v195, v196
	v_cvt_pk_bf16_f32 v148, v197, v198
	v_cvt_pk_bf16_f32 v149, v199, v200
	v_add_u32_e32 v154, 0xd000, v132
	s_waitcnt lgkmcnt(1)
	v_mfma_f32_16x16x32_bf16 v[68:71], v[142:145], v[146:149], v[68:71]
	v_add_f32_e32 v142, v160, v159
	v_add_f32_e32 v142, v161, v142
	ds_read_b128 v[154:157], v154 offset:512
	s_waitcnt lgkmcnt(1)
	v_mfma_f32_16x16x32_bf16 v[134:137], v[150:153], v[146:149], v[134:137]
	v_add_f32_e32 v150, v164, v142
	v_add_u32_e32 v142, 0xf000, v132
	ds_read_b128 v[142:145], v142 offset:768
	v_mov_b32_e32 v151, v150
	s_nop 1
	v_permlane16_swap_b32 v151, v150
	s_waitcnt lgkmcnt(0)
	v_mfma_f32_16x16x32_bf16 v[72:75], v[142:145], v[146:149], v[72:75]
	v_add_u32_e32 v142, 0x9000, v133
	ds_read_b128 v[142:145], v142
	v_add_f32_e32 v159, v150, v151
	v_mfma_f32_16x16x32_bf16 v[138:141], v[154:157], v[146:149], v[138:141]
	v_mov_b32_e32 v165, v159
	s_nop 1
	v_permlane32_swap_b32 v165, v159
	v_cvt_pk_bf16_f32 v146, v100, v202
	v_add_u32_e32 v100, 0xb000, v133
	ds_read_b128 v[150:153], v100 offset:256
	v_add_u32_e32 v100, 0xd000, v133
	v_fma_f32 v99, v99, s4, -v178
	ds_read_b128 v[154:157], v100 offset:512
	v_add_u32_e32 v100, 0xf000, v133
	v_exp_f32_e32 v99, v99
	v_cvt_pk_bf16_f32 v147, v163, v162
	v_cvt_pk_bf16_f32 v148, v158, v160
	v_cvt_pk_bf16_f32 v149, v161, v164
	v_writelane_b32 v244, s90, 62
	s_waitcnt lgkmcnt(2)
	v_mfma_f32_16x16x32_bf16 v[68:71], v[142:145], v[146:149], v[68:71]
	ds_read_b128 v[142:145], v100 offset:768
	v_add_f32_e32 v100, v159, v165
	v_add_f32_e32 v99, v99, v100
	v_rcp_f32_e32 v100, v99
	s_waitcnt lgkmcnt(2)
	v_mfma_f32_16x16x32_bf16 v[134:137], v[150:153], v[146:149], v[134:137]
	v_lshl_add_u32 v99, s90, 7, v109
	s_mov_b32 s16, 0xf149f2ca
	s_nop 0
	v_pk_mul_f32 v[70:71], v[70:71], v[100:101] op_sel_hi:[1,0]
	s_waitcnt lgkmcnt(1)
	v_mfma_f32_16x16x32_bf16 v[138:141], v[154:157], v[146:149], v[138:141]
	v_mul_f32_e64 v68, v68, v100
	v_mul_f32_e64 v69, v69, v100
	s_nop 0
	v_pk_mul_f32 v[134:135], v[134:135], v[100:101] op_sel_hi:[1,0]
	v_writelane_b32 v244, s91, 63
	s_waitcnt lgkmcnt(0)
	v_mfma_f32_16x16x32_bf16 v[72:75], v[142:145], v[146:149], v[72:75]
	v_mul_f32_e64 v142, v70, v70
	v_mul_f32_e64 v143, v71, v71
	v_pk_mul_f32 v[144:145], v[68:69], v[68:69]
	v_cvt_pk_bf16_f32 v68, v68, v69
	v_cvt_pk_bf16_f32 v69, v70, v71
	v_pk_mul_f32 v[70:71], v[136:137], v[100:101] op_sel_hi:[1,0]
	v_pk_mov_b32 v[146:147], v[144:145], v[142:143] op_sel:[1,0]
	v_mov_b32_e32 v145, v143
	v_pk_add_f32 v[142:143], v[146:147], v[144:145]
	v_pk_mul_f32 v[136:137], v[70:71], v[70:71]
	v_add_f32_e32 v142, v142, v143
	v_pk_mul_f32 v[144:145], v[134:135], v[134:135]
	v_cvt_pk_bf16_f32 v134, v134, v135
	v_cvt_pk_bf16_f32 v135, v70, v71
	v_pk_mul_f32 v[70:71], v[138:139], v[100:101] op_sel_hi:[1,0]
	v_add_f32_e32 v143, v110, v142
	v_pk_mov_b32 v[146:147], v[144:145], v[136:137] op_sel:[1,0]
	v_mov_b32_e32 v145, v137
	ds_write2_b64 v99, v[68:69], v[134:135] offset1:4
	v_pk_mul_f32 v[68:69], v[140:141], v[100:101] op_sel_hi:[1,0]
	v_mul_f32_e32 v110, v70, v70
	v_pk_add_f32 v[136:137], v[146:147], v[144:145]
	v_pk_fma_f32 v[134:135], v[70:71], v[70:71], v[110:111] op_sel_hi:[1,1,0]
	v_mul_f32_e32 v110, v68, v68
	v_pk_add_f32 v[136:137], v[136:137], v[136:137] op_sel_hi:[0,1]
	v_pk_fma_f32 v[138:139], v[68:69], v[68:69], v[110:111] op_sel_hi:[1,1,0]
	v_cvt_pk_bf16_f32 v70, v70, v71
	v_cvt_pk_bf16_f32 v71, v68, v69
	v_pk_mul_f32 v[68:69], v[74:75], v[100:101] op_sel_hi:[1,0]
	v_pk_mul_f32 v[72:73], v[72:73], v[100:101] op_sel_hi:[1,0]
	v_mul_f32_e32 v136, v68, v68
	v_mul_f32_e32 v134, v72, v72
	v_mul_f32_e32 v138, v73, v73
	v_mul_f32_e32 v142, v69, v69
	v_pk_add_f32 v[74:75], v[134:135], v[138:139]
	v_pk_add_f32 v[134:135], v[136:137], v[142:143]
	s_and_b64 vcc, exec, s[2:3]
	v_pk_add_f32 v[74:75], v[74:75], v[134:135]
	s_mov_b32 s90, 1
	v_add_f32_e32 v110, v74, v75
	s_mov_b64 s[2:3], 0
	v_cvt_pk_bf16_f32 v72, v72, v73
	v_cvt_pk_bf16_f32 v73, v68, v69
	ds_write2_b64 v99, v[70:71], v[72:73] offset0:8 offset1:12
	s_cbranch_vccnz .LBB0_181

.LBB0_209:
	ds_read_b128 v[172:175], v136
	ds_read_b128 v[176:179], v136 offset:64
	ds_read_b128 v[196:199], v136 offset:2304
	ds_read_b128 v[200:203], v136 offset:2368
	ds_read_b128 v[204:207], v136 offset:4672
	ds_read_b128 v[208:211], v136 offset:4608
	ds_read_b128 v[212:215], v136 offset:6912
	ds_read_b128 v[216:219], v136 offset:6976
	s_add_u32 s0, s0, 64
	s_addc_u32 s1, s1, 0
	s_waitcnt lgkmcnt(7)
	v_mfma_f32_16x16x32_bf16 v[48:51], v[172:175], v[104:107], 0
	ds_read_b128 v[220:223], v136 offset:9216
	s_add_u32 s4, s4, 0x80
	s_addc_u32 s5, s5, 0
	s_cmpk_lg_i32 s4, 0x200
	s_waitcnt lgkmcnt(6)
	v_mfma_f32_16x16x32_bf16 v[56:59], v[196:199], v[104:107], 0
	ds_read_b128 v[172:175], v136 offset:11520
	v_mfma_f32_16x16x32_bf16 v[108:111], v[176:179], v[44:47], v[48:51]
	ds_read_b128 v[196:199], v136 offset:9280
	s_nop 1
	s_waitcnt lgkmcnt(7)
	v_mfma_f32_16x16x32_bf16 v[100:103], v[200:203], v[44:47], v[56:59]
	ds_read_b128 v[176:179], v136 offset:11584
	s_nop 2
	s_waitcnt lgkmcnt(6)
	v_mfma_f32_16x16x32_bf16 v[48:51], v[208:211], v[104:107], 0
	ds_read_b128 v[200:203], v136 offset:13888
	v_mfma_f32_16x16x32_bf16 v[96:99], v[204:207], v[44:47], v[48:51]
	ds_read_b128 v[208:211], v136 offset:13824
	s_nop 6
	s_waitcnt lgkmcnt(7)
	v_mfma_f32_16x16x32_bf16 v[52:55], v[212:215], v[104:107], 0
	ds_read_b128 v[204:207], v136 offset:16128
	s_waitcnt lgkmcnt(7)
	v_mfma_f32_16x16x32_bf16 v[92:95], v[216:219], v[44:47], v[52:55]
	ds_read_b128 v[212:215], v136 offset:16192
	s_waitcnt lgkmcnt(7)
	v_mfma_f32_16x16x32_bf16 v[52:55], v[220:223], v[104:107], 0
	ds_read_b128 v[216:219], v136 offset:18432
	s_waitcnt lgkmcnt(6)
	v_mfma_f32_16x16x32_bf16 v[88:91], v[196:199], v[44:47], v[52:55]
	ds_read_b128 v[220:223], v136 offset:18496
	s_nop 0
	v_mfma_f32_16x16x32_bf16 v[52:55], v[172:175], v[104:107], 0
	ds_read_b128 v[196:199], v136 offset:20736
	s_waitcnt lgkmcnt(7)
	v_mfma_f32_16x16x32_bf16 v[84:87], v[176:179], v[44:47], v[52:55]
	ds_read_b128 v[172:175], v136 offset:20800
	s_waitcnt lgkmcnt(6)
	v_mfma_f32_16x16x32_bf16 v[52:55], v[208:211], v[104:107], 0
	ds_read_b128 v[176:179], v136 offset:23040
	v_mfma_f32_16x16x32_bf16 v[80:83], v[200:203], v[44:47], v[52:55]
	ds_read_b128 v[208:211], v136 offset:23104
	s_waitcnt lgkmcnt(7)
	s_nop 0
	v_mfma_f32_16x16x32_bf16 v[52:55], v[204:207], v[104:107], 0
	ds_read_b128 v[200:203], v136 offset:25344
	s_waitcnt lgkmcnt(7)
	v_mfma_f32_16x16x32_bf16 v[76:79], v[212:215], v[44:47], v[52:55]
	ds_read_b128 v[204:207], v136 offset:25408
	s_waitcnt lgkmcnt(7)
	v_mfma_f32_16x16x32_bf16 v[52:55], v[216:219], v[104:107], 0
	ds_read_b128 v[212:215], v136 offset:27648
	s_waitcnt lgkmcnt(7)
	v_mfma_f32_16x16x32_bf16 v[68:71], v[220:223], v[44:47], v[52:55]
	ds_read_b128 v[216:219], v136 offset:27712
	s_waitcnt lgkmcnt(7)
	v_mfma_f32_16x16x32_bf16 v[52:55], v[196:199], v[104:107], 0
	ds_read_b128 v[220:223], v136 offset:29952
	s_waitcnt lgkmcnt(6)
	v_mfma_f32_16x16x32_bf16 v[56:59], v[176:179], v[104:107], 0
	ds_read_b128 v[196:199], v136 offset:32256
	s_waitcnt lgkmcnt(6)
	v_mfma_f32_16x16x32_bf16 v[72:75], v[208:211], v[44:47], v[56:59]
	ds_read_b128 v[176:179], v136 offset:32320
	v_mfma_f32_16x16x32_bf16 v[64:67], v[172:175], v[44:47], v[52:55]
	ds_read_b128 v[208:211], v136 offset:30016
	s_nop 4
	v_max3_f32 v56, v108, s16, v109
	v_max3_f32 v56, v56, v110, v111
	v_max3_f32 v60, v56, v100, v101
	s_waitcnt lgkmcnt(7)
	v_mfma_f32_16x16x32_bf16 v[56:59], v[200:203], v[104:107], 0
	ds_read_b128 v[172:175], v136 offset:34560
	v_max3_f32 v60, v60, v102, v103
	v_max3_f32 v60, v60, v96, v97
	v_max3_f32 v138, v60, v98, v99
	s_waitcnt lgkmcnt(7)
	v_mfma_f32_16x16x32_bf16 v[60:63], v[204:207], v[44:47], v[56:59]
	ds_read_b128 v[200:203], v136 offset:34624
	v_max3_f32 v56, v138, v92, v93
	v_max3_f32 v56, v56, v94, v95
	v_max3_f32 v56, v56, v88, v89
	s_waitcnt lgkmcnt(7)
	v_mfma_f32_16x16x32_bf16 v[48:51], v[212:215], v[104:107], 0
	ds_read_b128 v[204:207], v240
	v_max3_f32 v56, v56, v90, v91
	v_max3_f32 v56, v56, v84, v85
	v_max3_f32 v138, v56, v86, v87
	s_waitcnt lgkmcnt(7)
	v_mfma_f32_16x16x32_bf16 v[56:59], v[216:219], v[44:47], v[48:51]
	ds_read_b128 v[212:215], v241
	s_nop 2
	v_max3_f32 v48, v138, v80, v81
	v_max3_f32 v48, v48, v82, v83
	v_max3_f32 v52, v48, v76, v77
	s_waitcnt lgkmcnt(7)
	v_mfma_f32_16x16x32_bf16 v[48:51], v[220:223], v[104:107], 0
	ds_read_b128 v[216:219], v242 offset:256
	v_max3_f32 v52, v52, v78, v79
	v_max3_f32 v52, v52, v68, v69
	v_max3_f32 v138, v52, v70, v71
	s_waitcnt lgkmcnt(5)
	v_mfma_f32_16x16x32_bf16 v[52:55], v[208:211], v[44:47], v[48:51]
	ds_read_b128 v[220:223], v245 offset:512
	s_nop 2
	v_max3_f32 v48, v138, v64, v65
	v_max3_f32 v48, v48, v66, v67
	v_max3_f32 v138, v48, v72, v73
	s_nop 0
	v_mfma_f32_16x16x32_bf16 v[48:51], v[196:199], v[104:107], 0
	ds_read_b128 v[208:211], v240 offset:64
	v_max3_f32 v138, v138, v74, v75
	v_max3_f32 v138, v138, v60, v61
	v_max3_f32 v138, v138, v62, v63
	s_waitcnt lgkmcnt(6)
	v_mfma_f32_16x16x32_bf16 v[104:107], v[172:175], v[104:107], 0
	ds_read_b128 v[196:199], v241 offset:64
	v_max3_f32 v138, v138, v56, v57
	v_max3_f32 v138, v138, v58, v59
	v_max3_f32 v138, v138, v52, v53
	v_mfma_f32_16x16x32_bf16 v[48:51], v[176:179], v[44:47], v[48:51]
	ds_read_b128 v[172:175], v242 offset:320
	v_max3_f32 v138, v138, v54, v55
	s_waitcnt lgkmcnt(7)
	v_mfma_f32_16x16x32_bf16 v[44:47], v[200:203], v[44:47], v[104:107]
	ds_read_b128 v[176:179], v245 offset:576
	s_nop 4
	v_max3_f32 v138, v138, v48, v49
	v_max3_f32 v138, v138, v50, v51
	s_nop 0
	v_max3_f32 v104, v138, v44, v45
	v_max3_f32 v104, v104, v46, v47
	v_mov_b32_e32 v105, v104
	s_nop 1
	v_permlane16_swap_b32 v105, v104
	s_nop 0
	v_max_f32_e32 v105, v105, v105
	v_max_f32_e32 v104, v104, v105
	v_mov_b32_e32 v105, v104
	s_nop 1
	v_permlane32_swap_b32 v105, v104
	s_nop 0
	v_max_f32_e32 v105, v105, v105
	v_max_f32_e32 v104, v104, v105
	v_sub_f32_e32 v105, v108, v104
	v_exp_f32_e32 v106, v105
	v_sub_f32_e32 v105, v109, v104
	v_exp_f32_e32 v107, v105
	v_sub_f32_e32 v105, v110, v104
	v_exp_f32_e32 v108, v105
	v_sub_f32_e32 v105, v111, v104
	v_exp_f32_e32 v110, v105
	v_sub_f32_e32 v100, v100, v104
	v_add_f32_e32 v105, 0, v106
	v_exp_f32_e32 v109, v100
	v_sub_f32_e32 v100, v101, v104
	v_add_f32_e32 v105, v107, v105
	v_exp_f32_e32 v111, v100
	v_sub_f32_e32 v100, v102, v104
	v_add_f32_e32 v105, v108, v105
	v_exp_f32_e32 v138, v100
	v_sub_f32_e32 v100, v103, v104
	v_add_f32_e32 v105, v110, v105
	v_exp_f32_e32 v139, v100
	v_add_f32_e32 v100, v109, v105
	v_add_f32_e32 v100, v111, v100
	v_add_f32_e32 v100, v138, v100
	v_sub_f32_e32 v96, v96, v104
	v_add_f32_e32 v102, v139, v100
	v_exp_f32_e32 v100, v96
	v_sub_f32_e32 v96, v97, v104
	v_exp_f32_e32 v101, v96
	v_sub_f32_e32 v96, v98, v104
	v_exp_f32_e32 v97, v96
	v_sub_f32_e32 v96, v99, v104
	v_exp_f32_e32 v98, v96
	v_sub_f32_e32 v92, v92, v104
	v_add_f32_e32 v96, v100, v102
	v_exp_f32_e32 v99, v92
	v_sub_f32_e32 v92, v93, v104
	v_add_f32_e32 v96, v101, v96
	v_exp_f32_e32 v102, v92
	v_sub_f32_e32 v92, v94, v104
	v_add_f32_e32 v96, v97, v96
	v_exp_f32_e32 v103, v92
	v_sub_f32_e32 v92, v95, v104
	v_add_f32_e32 v96, v98, v96
	v_exp_f32_e32 v105, v92
	v_add_f32_e32 v92, v99, v96
	v_add_f32_e32 v92, v102, v92
	v_add_f32_e32 v92, v103, v92
	v_sub_f32_e32 v88, v88, v104
	v_add_f32_e32 v94, v105, v92
	v_exp_f32_e32 v92, v88
	v_sub_f32_e32 v88, v89, v104
	v_exp_f32_e32 v93, v88
	v_sub_f32_e32 v88, v90, v104
	v_exp_f32_e32 v89, v88
	v_sub_f32_e32 v88, v91, v104
	v_exp_f32_e32 v90, v88
	v_sub_f32_e32 v84, v84, v104
	v_add_f32_e32 v88, v92, v94
	v_exp_f32_e32 v91, v84
	v_sub_f32_e32 v84, v85, v104
	v_add_f32_e32 v88, v93, v88
	v_exp_f32_e32 v94, v84
	v_sub_f32_e32 v84, v86, v104
	v_add_f32_e32 v88, v89, v88
	v_exp_f32_e32 v95, v84
	v_sub_f32_e32 v84, v87, v104
	v_add_f32_e32 v88, v90, v88
	v_exp_f32_e32 v96, v84
	v_add_f32_e32 v84, v91, v88
	v_add_f32_e32 v84, v94, v84
	v_add_f32_e32 v84, v95, v84
	v_sub_f32_e32 v80, v80, v104
	v_add_f32_e32 v86, v96, v84
	v_exp_f32_e32 v84, v80
	v_sub_f32_e32 v80, v81, v104
	v_exp_f32_e32 v85, v80
	v_sub_f32_e32 v80, v82, v104
	v_exp_f32_e32 v81, v80
	v_sub_f32_e32 v80, v83, v104
	v_exp_f32_e32 v82, v80
	v_sub_f32_e32 v76, v76, v104
	v_add_f32_e32 v80, v84, v86
	v_exp_f32_e32 v83, v76
	v_sub_f32_e32 v76, v77, v104
	v_add_f32_e32 v80, v85, v80
	v_exp_f32_e32 v86, v76
	v_sub_f32_e32 v76, v78, v104
	v_add_f32_e32 v80, v81, v80
	v_exp_f32_e32 v87, v76
	v_sub_f32_e32 v76, v79, v104
	v_add_f32_e32 v80, v82, v80
	v_exp_f32_e32 v88, v76
	v_add_f32_e32 v76, v83, v80
	v_add_f32_e32 v76, v86, v76
	v_add_f32_e32 v76, v87, v76
	v_sub_f32_e32 v68, v68, v104
	v_add_f32_e32 v78, v88, v76
	v_exp_f32_e32 v76, v68
	v_sub_f32_e32 v68, v69, v104
	v_exp_f32_e32 v77, v68
	v_sub_f32_e32 v68, v70, v104
	v_exp_f32_e32 v68, v68
	v_sub_f32_e32 v69, v71, v104
	v_exp_f32_e32 v69, v69
	v_sub_f32_e32 v64, v64, v104
	v_add_f32_e32 v70, v76, v78
	v_exp_f32_e32 v71, v64
	v_sub_f32_e32 v64, v65, v104
	v_add_f32_e32 v70, v77, v70
	v_exp_f32_e32 v78, v64
	v_sub_f32_e32 v64, v66, v104
	v_add_f32_e32 v70, v68, v70
	v_exp_f32_e32 v79, v64
	v_sub_f32_e32 v64, v67, v104
	v_add_f32_e32 v70, v69, v70
	v_exp_f32_e32 v80, v64
	v_add_f32_e32 v64, v71, v70
	v_add_f32_e32 v64, v78, v64
	v_add_f32_e32 v64, v79, v64
	v_add_f32_e32 v70, v80, v64
	v_sub_f32_e32 v64, v72, v104
	v_exp_f32_e32 v65, v64
	v_sub_f32_e32 v64, v73, v104
	v_exp_f32_e32 v67, v64
	v_sub_f32_e32 v64, v74, v104
	v_exp_f32_e32 v64, v64
	v_sub_f32_e32 v66, v75, v104
	v_exp_f32_e32 v66, v66
	v_sub_f32_e32 v60, v60, v104
	v_add_f32_e32 v70, v65, v70
	v_exp_f32_e32 v60, v60
	v_sub_f32_e32 v61, v61, v104
	v_add_f32_e32 v70, v67, v70
	v_exp_f32_e32 v61, v61
	v_sub_f32_e32 v62, v62, v104
	v_add_f32_e32 v70, v64, v70
	v_exp_f32_e32 v62, v62
	v_sub_f32_e32 v63, v63, v104
	v_add_f32_e32 v70, v66, v70
	v_exp_f32_e32 v63, v63
	v_add_f32_e32 v70, v60, v70
	v_add_f32_e32 v70, v61, v70
	v_add_f32_e32 v70, v62, v70
	v_add_f32_e32 v75, v63, v70
	v_sub_f32_e32 v56, v56, v104
	v_add_u32_e32 v70, v133, v115
	v_add_u32_e32 v73, 0x9000, v70
	v_add_u32_e32 v72, 0x9000, v137
	v_add_u32_e32 v70, 0xb000, v137
	v_exp_f32_e32 v74, v56
	v_add_u32_e32 v56, 0xd000, v137
	v_cvt_pk_bf16_f32 v106, v106, v107
	v_cvt_pk_bf16_f32 v107, v108, v110
	v_cvt_pk_bf16_f32 v108, v109, v111
	v_cvt_pk_bf16_f32 v109, v138, v139
	s_waitcnt lgkmcnt(7)
	s_nop 0
	v_mfma_f32_16x16x32_bf16 v[138:141], v[204:207], v[106:109], 0
	ds_read_b128 v[200:203], v240 offset:128
	v_cvt_pk_bf16_f32 v100, v100, v101
	v_cvt_pk_bf16_f32 v101, v97, v98
	v_cvt_pk_bf16_f32 v102, v99, v102
	s_waitcnt lgkmcnt(7)
	v_mfma_f32_16x16x32_bf16 v[142:145], v[212:215], v[106:109], 0
	ds_read_b128 v[204:207], v242 offset:384
	v_cvt_pk_bf16_f32 v103, v103, v105
	v_cvt_pk_bf16_f32 v92, v92, v93
	s_waitcnt lgkmcnt(7)
	v_mfma_f32_16x16x32_bf16 v[146:149], v[216:219], v[106:109], 0
	ds_read_b128 v[212:215], v241 offset:128
	v_cvt_pk_bf16_f32 v93, v89, v90
	v_cvt_pk_bf16_f32 v94, v91, v94
	v_cvt_pk_bf16_f32 v95, v95, v96
	s_waitcnt lgkmcnt(7)
	v_mfma_f32_16x16x32_bf16 v[106:109], v[220:223], v[106:109], 0
	ds_read_b128 v[216:219], v245 offset:640
	v_cvt_pk_bf16_f32 v84, v84, v85
	v_cvt_pk_bf16_f32 v85, v81, v82
	s_waitcnt lgkmcnt(7)
	v_mfma_f32_16x16x32_bf16 v[138:141], v[208:211], v[100:103], v[138:141]
	ds_read_b128 v[220:223], v240 offset:192
	v_cvt_pk_bf16_f32 v86, v83, v86
	v_cvt_pk_bf16_f32 v87, v87, v88
	s_waitcnt lgkmcnt(7)
	v_mfma_f32_16x16x32_bf16 v[142:145], v[196:199], v[100:103], v[142:145]
	ds_read_b128 v[208:211], v242 offset:448
	v_sub_f32_e32 v57, v57, v104
	v_cvt_pk_bf16_f32 v76, v76, v77
	s_waitcnt lgkmcnt(7)
	v_mfma_f32_16x16x32_bf16 v[146:149], v[172:175], v[100:103], v[146:149]
	ds_read_b128 v[196:199], v241 offset:192
	v_cvt_pk_bf16_f32 v77, v68, v69
	v_cvt_pk_bf16_f32 v78, v71, v78
	v_cvt_pk_bf16_f32 v79, v79, v80
	s_waitcnt lgkmcnt(7)
	v_mfma_f32_16x16x32_bf16 v[98:101], v[176:179], v[100:103], v[106:109]
	ds_read_b128 v[172:175], v245 offset:704
	v_exp_f32_e32 v57, v57
	v_sub_f32_e32 v58, v58, v104
	s_waitcnt lgkmcnt(7)
	v_mfma_f32_16x16x32_bf16 v[138:141], v[200:203], v[92:95], v[138:141]
	ds_read_b128 v[176:179], v240 offset:256
	v_exp_f32_e32 v58, v58
	v_sub_f32_e32 v59, v59, v104
	s_waitcnt lgkmcnt(6)
	v_mfma_f32_16x16x32_bf16 v[106:109], v[212:215], v[92:95], v[142:145]
	ds_read_b128 v[200:203], v242 offset:512
	v_exp_f32_e32 v59, v59
	v_sub_f32_e32 v52, v52, v104
	v_add_f32_e32 v75, v74, v75
	v_mfma_f32_16x16x32_bf16 v[142:145], v[204:207], v[92:95], v[146:149]
	ds_read_b128 v[212:215], v241 offset:256
	v_exp_f32_e32 v52, v52
	v_sub_f32_e32 v53, v53, v104
	v_add_f32_e32 v75, v57, v75
	s_waitcnt lgkmcnt(7)
	v_mfma_f32_16x16x32_bf16 v[90:93], v[216:219], v[92:95], v[98:101]
	ds_read_b128 v[204:207], v245 offset:768
	v_exp_f32_e32 v53, v53
	v_sub_f32_e32 v54, v54, v104
	s_waitcnt lgkmcnt(7)
	v_mfma_f32_16x16x32_bf16 v[138:141], v[220:223], v[84:87], v[138:141]
	ds_read_b128 v[216:219], v241 offset:320
	v_add_f32_e32 v75, v58, v75
	v_exp_f32_e32 v54, v54
	s_waitcnt lgkmcnt(6)
	v_mfma_f32_16x16x32_bf16 v[94:97], v[196:199], v[84:87], v[106:109]
	ds_read_b128 v[220:223], v245 offset:832
	v_sub_f32_e32 v55, v55, v104
	v_add_f32_e32 v75, v59, v75
	v_exp_f32_e32 v55, v55
	v_mfma_f32_16x16x32_bf16 v[98:101], v[208:211], v[84:87], v[142:145]
	ds_read_b128 v[196:199], v242 offset:576
	v_sub_f32_e32 v48, v48, v104
	v_add_f32_e32 v75, v52, v75
	v_exp_f32_e32 v102, v48
	s_waitcnt lgkmcnt(7)
	v_mfma_f32_16x16x32_bf16 v[82:85], v[172:175], v[84:87], v[90:93]
	ds_read_b128 v[208:211], v240 offset:320
	v_sub_f32_e32 v48, v49, v104
	v_add_f32_e32 v75, v53, v75
	s_waitcnt lgkmcnt(7)
	v_mfma_f32_16x16x32_bf16 v[106:109], v[176:179], v[76:79], v[138:141]
	ds_read_b128 v[172:175], v240 offset:384
	v_exp_f32_e32 v103, v48
	v_sub_f32_e32 v48, v50, v104
	v_add_f32_e32 v75, v54, v75
	s_waitcnt lgkmcnt(6)
	v_mfma_f32_16x16x32_bf16 v[86:89], v[212:215], v[76:79], v[94:97]
	ds_read_b128 v[176:179], v242 offset:640
	v_exp_f32_e32 v68, v48
	v_add_f32_e32 v75, v55, v75
	v_cvt_pk_bf16_f32 v80, v65, v67
	v_mfma_f32_16x16x32_bf16 v[90:93], v[200:203], v[76:79], v[98:101]
	ds_read_b128 v[212:215], v241 offset:384
	v_cvt_pk_bf16_f32 v81, v64, v66
	s_waitcnt lgkmcnt(7)
	v_mfma_f32_16x16x32_bf16 v[76:79], v[204:207], v[76:79], v[82:85]
	ds_read_b128 v[200:203], v245 offset:896
	v_cvt_pk_bf16_f32 v82, v60, v61
	v_cvt_pk_bf16_f32 v83, v62, v63
	v_add_f32_e32 v48, v102, v75
	v_add_f32_e32 v48, v103, v48
	v_add_f32_e32 v69, v68, v48
	v_sub_f32_e32 v71, v51, v104
	s_waitcnt lgkmcnt(7)
	v_mfma_f32_16x16x32_bf16 v[84:87], v[216:219], v[80:83], v[86:89]
	ds_read_b128 v[204:207], v240 offset:448
	v_exp_f32_e32 v71, v71
	v_sub_f32_e32 v44, v44, v104
	v_exp_f32_e32 v94, v44
	s_waitcnt lgkmcnt(6)
	v_mfma_f32_16x16x32_bf16 v[60:63], v[196:199], v[80:83], v[90:93]
	ds_read_b128 v[216:219], v242 offset:704
	v_sub_f32_e32 v44, v45, v104
	v_exp_f32_e32 v95, v44
	v_sub_f32_e32 v45, v46, v104
	v_mfma_f32_16x16x32_bf16 v[64:67], v[220:223], v[80:83], v[76:79]
	ds_read_b128 v[196:199], v241 offset:448
	v_cvt_pk_bf16_f32 v76, v52, v53
	v_cvt_pk_bf16_f32 v77, v54, v55
	s_waitcnt lgkmcnt(7)
	v_mfma_f32_16x16x32_bf16 v[48:51], v[208:211], v[80:83], v[106:109]
	ds_read_b128 v[220:223], v245 offset:960
	v_add_f32_e32 v69, v71, v69
	v_cvt_pk_bf16_f32 v74, v74, v57
	v_exp_f32_e32 v57, v45
	v_sub_f32_e32 v45, v47, v104
	v_add_f32_e32 v44, v94, v69
	v_exp_f32_e32 v69, v45
	v_add_f32_e32 v44, v95, v44
	v_cvt_pk_bf16_f32 v75, v58, v59
	s_nop 0
	v_add_f32_e32 v58, v57, v44
	s_waitcnt lgkmcnt(7)
	v_mfma_f32_16x16x32_bf16 v[48:51], v[172:175], v[74:77], v[48:51]
	s_waitcnt lgkmcnt(6)
	v_mfma_f32_16x16x32_bf16 v[44:47], v[176:179], v[74:77], v[60:63]
	v_add_f32_e32 v73, v69, v58
	v_mov_b32_e32 v82, v73
	s_nop 1
	v_permlane16_swap_b32 v82, v73
	v_cvt_pk_bf16_f32 v69, v57, v69
	s_waitcnt lgkmcnt(5)
	v_mfma_f32_16x16x32_bf16 v[78:81], v[212:215], v[74:77], v[84:87]
	v_add_f32_e32 v57, v73, v82
	s_waitcnt lgkmcnt(4)
	v_mfma_f32_16x16x32_bf16 v[58:61], v[200:203], v[74:77], v[64:67]
	v_mov_b32_e32 v74, v57
	s_nop 1
	v_permlane32_swap_b32 v74, v57
	v_cvt_pk_bf16_f32 v66, v102, v103
	v_cvt_pk_bf16_f32 v67, v68, v71
	v_cvt_pk_bf16_f32 v68, v94, v95
	s_nop 0
	s_waitcnt lgkmcnt(3)
	v_mfma_f32_16x16x32_bf16 v[48:51], v[204:207], v[66:69], v[48:51]
	v_add_f32_e32 v56, v57, v74
	v_rcp_f32_e32 v56, v56
	s_waitcnt lgkmcnt(1)
	v_mfma_f32_16x16x32_bf16 v[62:65], v[196:199], v[66:69], v[78:81]
	s_nop 3
	v_mul_f32_e64 v50, v56, v50
	v_mul_f32_e64 v51, v56, v51
	v_pk_mul_f32 v[48:49], v[56:57], v[48:49] op_sel_hi:[0,1]
	v_mfma_f32_16x16x32_bf16 v[44:47], v[216:219], v[66:69], v[44:47]
	s_waitcnt lgkmcnt(0)
	v_mfma_f32_16x16x32_bf16 v[52:55], v[220:223], v[66:69], v[58:61]
	s_nop 2
	v_mul_f32_e64 v58, v50, v50
	v_mul_f32_e64 v59, v51, v51
	v_pk_mul_f32 v[60:61], v[48:49], v[48:49]
	v_cvt_pk_bf16_f32 v48, v48, v49
	v_cvt_pk_bf16_f32 v49, v50, v51
	s_nop 0
	v_pk_mov_b32 v[66:67], v[60:61], v[58:59] op_sel:[1,0]
	v_mov_b32_e32 v61, v59
	v_pk_add_f32 v[58:59], v[66:67], v[60:61]
	s_nop 0
	v_add_f32_e32 v57, v58, v59
	v_pk_mul_f32 v[50:51], v[56:57], v[64:65] op_sel_hi:[0,1]
	v_pk_mul_f32 v[60:61], v[56:57], v[62:63] op_sel_hi:[0,1]
	v_pk_mul_f32 v[62:63], v[50:51], v[50:51]
	v_pk_mul_f32 v[64:65], v[60:61], v[60:61]
	v_pk_mul_f32 v[52:53], v[56:57], v[52:53] op_sel_hi:[0,1]
	v_pk_mov_b32 v[66:67], v[64:65], v[62:63] op_sel:[1,0]
	v_mov_b32_e32 v65, v63
	v_pk_add_f32 v[62:63], v[66:67], v[64:65]
	v_cvt_pk_bf16_f32 v60, v60, v61
	v_cvt_pk_bf16_f32 v61, v50, v51
	v_pk_mul_f32 v[46:47], v[56:57], v[46:47] op_sel_hi:[0,1]
	v_pk_mul_f32 v[44:45], v[56:57], v[44:45] op_sel_hi:[0,1]
	v_pk_mul_f32 v[50:51], v[56:57], v[54:55] op_sel_hi:[0,1]
	v_mul_f32_e32 v56, v53, v53
	v_pk_add_f32 v[54:55], v[62:63], v[62:63] op_sel:[0,1] op_sel_hi:[1,0]
	v_add_f32_e32 v58, v130, v57
	v_mul_f32_e32 v57, v50, v50
	v_mov_b32_e32 v55, v56
	v_mul_f32_e32 v56, v45, v45
	ds_write2_b64 v134, v[48:49], v[60:61] offset1:4
	v_cvt_pk_bf16_f32 v48, v44, v45
	v_pk_fma_f32 v[44:45], v[44:45], v[44:45], v[56:57] op_sel_hi:[1,1,0]
	v_mul_f32_e32 v56, v47, v47
	v_cvt_pk_bf16_f32 v49, v46, v47
	v_mul_f32_e32 v60, v51, v51
	v_pk_fma_f32 v[46:47], v[46:47], v[46:47], v[56:57] op_sel_hi:[1,1,0]
	v_mul_f32_e32 v59, v52, v52
	v_mov_b32_e32 v45, v57
	v_mov_b32_e32 v47, v60
	v_pk_add_f32 v[54:55], v[58:59], v[54:55]
	v_pk_add_f32 v[44:45], v[44:45], v[46:47]
	s_nop 0
	v_pk_add_f32 v[44:45], v[54:55], v[44:45]
	s_nop 0
	v_add_f32_e32 v130, v44, v45
	v_cvt_pk_bf16_f32 v44, v52, v53
	v_cvt_pk_bf16_f32 v45, v50, v51
	ds_write2_b64 v134, v[48:49], v[44:45] offset0:8 offset1:12
	v_add_u32_e32 v134, 0x80, v134
	s_cbranch_scc0 .LBB0_215
